# grid barrier: non-leader blocks poll the global release flag directly instead of waiting for the per-XCD relay flag (one hop less per barrier)
# speedup vs baseline: 1.0044x; 1.0032x over previous
.LBB0_1043:
	s_or_b64 exec, exec, s[2:3]
	s_waitcnt vmcnt(0)
	v_readfirstlane_b32 s2, v1
	v_readlane_b32 s3, v255, 10
	s_nop 0
	v_add3_u32 v0, s2, v0, 1
	v_readlane_b32 s2, v255, 6
	s_mul_i32 s2, s3, s2
	s_nop 0
	v_cmp_ne_u32_e32 vcc, s2, v0
	s_and_saveexec_b64 s[2:3], vcc
	s_xor_b64 s[2:3], exec, s[2:3]
	s_cbranch_execz .LBB0_1047
	v_readlane_b32 s4, v254, 23
	v_readlane_b32 s5, v254, 24
	v_readlane_b32 s6, v255, 10
	s_nop 3
	global_load_dword v0, v193, s[4:5] sc1
	s_waitcnt vmcnt(0)
	v_cmp_le_u32_e32 vcc, s6, v0
	s_cbranch_vccnz .LBB0_1046
